# v33 + attention key-row loop: the 8 exec-branch bias chains (branch, ds_read, full wait, add) replaced by 8 reads up front + v_cndmask
# speedup vs baseline: 1.0180x; 1.0014x over previous
; #define GAS __attribute__((address_space(1)))
; __device__ __forceinline__ void attn_load_k(AttnK& C, const GAS bf16* kbase  , int q, int g) {
; #pragma unroll
;     for (int T = 0; T < 2; ++T) { const unsigned koff = (unsigned)((8 * (q >> 2) + 4 * T + (q & 3)) * 2048 + 8 * g);
; #pragma unroll
;         for (int dc = 0; dc < 4; ++dc) C.kf[T][dc] = *(const GAS bf16x8*)(kbase + koff + 32 * dc); }
; }
; __device__ __forceinline__ void attn_load_v(AttnV& C, const GAS bf16* vbase  , int q, int g) {
;     const unsigned voff = (unsigned)(q * MT + 8 * g);
; #pragma unroll
; __device__ __forceinline__ void attn_compute(const AttnK& C, const AttnV& V, const bf16x8 (&qf)[4], f32x4 (&o)[8], float& mrun, float& lsum, int lane, int g,
;                                              bool masked, int keycol0, int cs, const LAS float* brow  , int cq) {
;     f32x4 s[2];
; #pragma unroll
;     for (int T = 0; T < 2; ++T) { s[T] = (f32x4){0.f, 0.f, 0.f, 0.f};
; #pragma unroll
;         for (int dc = 0; dc < 4; ++dc) s[T] = MFMA16(C.kf[T][dc], qf[dc], s[T]); }
;     if (masked) {
; #pragma unroll
;         for (int T = 0; T < 2; ++T)
; #pragma unroll
;             for (int i = 0; i < 4; ++i) { const int keycol = keycol0 + 8 * g + 4 * T + i; const bool ok = keycol >= cs && keycol < cs + 16;
;                 const int dcol = keycol - cq + 15; const float bv = brow[ok ? dcol : 0];
;                 s[T][i] = ok ? s[T][i] + bv : -1e30f; }
;     }
;     float cm = fmaxf(fmaxf(fmaxf(s[0][0], s[0][1]), fmaxf(s[0][2], s[0][3])), fmaxf(fmaxf(s[1][0], s[1][1]), fmaxf(s[1][2], s[1][3])));
;     cm = fmaxf(cm, lane_read(cm, lane ^ 16)); cm = fmaxf(cm, lane_read(cm, lane ^ 32));
;     const float mnew = fmaxf(mrun, cm), alpha = __builtin_amdgcn_exp2f(mrun - mnew);
;     mrun = mnew;
;     float p[8]; float ps = 0.f;
; #pragma unroll
;     for (int T = 0; T < 2; ++T)
; #pragma unroll
;         for (int i = 0; i < 4; ++i) { p[4 * T + i] = __builtin_amdgcn_exp2f(s[T][i] - mnew); ps += p[4 * T + i]; }
;     lsum = lsum * alpha + ps;
;     v4u pw; pw.x = pg8::cvt_pk_bf16(p[0], p[1]); pw.y = pg8::cvt_pk_bf16(p[2], p[3]); pw.z = pg8::cvt_pk_bf16(p[4], p[5]); pw.w = pg8::cvt_pk_bf16(p[6], p[7]);
;     const bf16x8 pf = __builtin_bit_cast(bf16x8, pw);
; #pragma unroll
;     for (int dt = 0; dt < 8; ++dt) { o[dt] = o[dt] * alpha; o[dt] = MFMA16(V.vf[dt], pf, o[dt]); }
; }
.LBB0_591:
	s_ashr_i32 s59, s58, 31
	s_lshl_b64 s[38:39], s[58:59], 12
	s_waitcnt vmcnt(0)
	v_lshl_add_u64 v[96:97], v[202:203], 0, s[38:39]
	global_load_dwordx4 v[128:131], v[96:97], off
	global_load_dwordx4 v[132:135], v[96:97], off offset:64
	global_load_dwordx4 v[136:139], v[96:97], off offset:128
	global_load_dwordx4 v[140:143], v[96:97], off offset:192
	v_add_co_u32_e32 v96, vcc, s48, v96
	s_mov_b32 s38, 0x104000
	s_nop 0
	v_addc_co_u32_e32 v97, vcc, 0, v97, vcc
	global_load_dwordx4 v[148:151], v[96:97], off
	global_load_dwordx4 v[152:155], v[96:97], off offset:64
	global_load_dwordx4 v[156:159], v[96:97], off offset:128
	global_load_dwordx4 v[144:147], v[96:97], off offset:192
	v_lshl_add_u64 v[96:97], s[58:59], 1, v[198:199]
	v_add_co_u32_e32 v98, vcc, s38, v96
	s_mov_b32 s38, 0x208000
	s_nop 0
	v_addc_co_u32_e32 v99, vcc, 0, v97, vcc
	global_load_dwordx4 v[124:127], v[96:97], off
	global_load_dwordx4 v[116:119], v[98:99], off
	v_add_co_u32_e32 v98, vcc, s38, v96
	s_mov_b32 s38, 0x30c000
	s_nop 0
	v_addc_co_u32_e32 v99, vcc, 0, v97, vcc
	v_add_co_u32_e32 v100, vcc, s38, v96
	s_mov_b32 s38, 0x410000
	s_nop 0
	v_addc_co_u32_e32 v101, vcc, 0, v97, vcc
	global_load_dwordx4 v[120:123], v[98:99], off
	global_load_dwordx4 v[108:111], v[100:101], off
	v_add_co_u32_e32 v98, vcc, s38, v96
	s_cmp_ge_u32 s78, s94
	s_nop 0
	v_addc_co_u32_e32 v99, vcc, 0, v97, vcc
	v_add_co_u32_e32 v100, vcc, 0x514000, v96
	s_nop 1
	v_addc_co_u32_e32 v101, vcc, 0, v97, vcc
	global_load_dwordx4 v[112:115], v[98:99], off
	global_load_dwordx4 v[104:107], v[100:101], off
	v_add_co_u32_e32 v98, vcc, 0x618000, v96
	s_nop 1
	v_addc_co_u32_e32 v99, vcc, 0, v97, vcc
	v_add_co_u32_e32 v96, vcc, 0x71c000, v96
	s_nop 1
	v_addc_co_u32_e32 v97, vcc, 0, v97, vcc
	global_load_dwordx4 v[100:103], v[98:99], off
	s_nop 0
	global_load_dwordx4 v[96:99], v[96:97], off
	s_cbranch_scc1 .LBB0_609
	s_waitcnt vmcnt(0)
	v_mfma_f32_16x16x32_bf16 v[160:163], v[128:131], v[60:63], 0
	v_mov_b32_e32 v178, 0xf149f2ca
	v_mov_b32_e32 v179, 0xf149f2ca
	v_mfma_f32_16x16x32_bf16 v[160:163], v[132:135], v[68:71], v[160:163]
	v_mfma_f32_16x16x32_bf16 v[160:163], v[136:139], v[80:83], v[160:163]
	v_mfma_f32_16x16x32_bf16 v[164:167], v[140:143], v[84:87], v[160:163]
	v_mfma_f32_16x16x32_bf16 v[160:163], v[148:151], v[60:63], 0
	v_mfma_f32_16x16x32_bf16 v[160:163], v[152:155], v[68:71], v[160:163]
	v_mfma_f32_16x16x32_bf16 v[160:163], v[156:159], v[80:83], v[160:163]
	v_mfma_f32_16x16x32_bf16 v[160:163], v[144:147], v[84:87], v[160:163]
	ds_read_b32 v179, v249 offset:124
	ds_read_b32 v178, v249 offset:128
	ds_read_b32 v218, v249 offset:132
	ds_read_b32 v219, v249 offset:136
	ds_read_b32 v222, v249 offset:140
	ds_read_b32 v223, v249 offset:144
	ds_read_b32 v233, v249 offset:148
	ds_read_b32 v234, v249 offset:152
	v_mov_b32_e32 v235, 0xf149f2ca
	s_waitcnt lgkmcnt(0)
	v_add_f32_e32 v179, v164, v179
	v_add_f32_e32 v178, v165, v178
	v_add_f32_e32 v218, v166, v218
	v_add_f32_e32 v219, v167, v219
	v_add_f32_e32 v222, v160, v222
	v_add_f32_e32 v223, v161, v223
	v_add_f32_e32 v233, v162, v233
	v_add_f32_e32 v234, v163, v234
	v_cndmask_b32_e64 v179, v235, v179, s[18:19]
	v_cndmask_b32_e64 v178, v235, v178, s[20:21]
	v_cndmask_b32_e64 v218, v235, v218, s[22:23]
	v_cndmask_b32_e64 v164, v235, v219, s[24:25]
	v_cndmask_b32_e64 v166, v235, v222, s[26:27]
	v_cndmask_b32_e64 v165, v235, v223, s[28:29]
	v_cndmask_b32_e64 v161, v235, v233, s[30:31]
	v_cndmask_b32_e64 v160, v235, v234, s[34:35]
	v_max_f32_e32 v162, v179, v178
	v_max_f32_e32 v163, v218, v164
	v_max_f32_e32 v167, v161, v160
	v_max3_f32 v167, v166, v165, v167
	v_max3_f32 v162, v162, v163, v167
	ds_bpermute_b32 v163, v171, v162
	s_waitcnt lgkmcnt(0)
	v_max_f32_e32 v163, v163, v163
	v_max_f32_e32 v162, v162, v163
	ds_bpermute_b32 v163, v185, v162
	s_waitcnt lgkmcnt(0)
	v_max3_f32 v167, v248, v162, v163
	v_sub_f32_e32 v163, v179, v167
	v_exp_f32_e32 v163, v163
	v_sub_f32_e32 v178, v178, v167
	v_exp_f32_e32 v178, v178
	v_sub_f32_e32 v218, v218, v167
	v_exp_f32_e32 v218, v218
	v_sub_f32_e32 v164, v164, v167
	v_exp_f32_e32 v219, v164
	v_add_f32_e32 v179, 0, v163
	v_sub_f32_e32 v166, v166, v167
	v_add_f32_e32 v179, v178, v179
	v_exp_f32_e32 v166, v166
	v_sub_f32_e32 v165, v165, v167
	v_add_f32_e32 v179, v218, v179
	v_exp_f32_e32 v165, v165
	v_sub_f32_e32 v161, v161, v167
	v_add_f32_e32 v164, v219, v179
	v_exp_f32_e32 v179, v161
	v_add_f32_e32 v164, v166, v164
	v_sub_f32_e32 v162, v248, v167
	v_add_f32_e32 v164, v165, v164
	v_add_f32_e32 v161, v179, v164
	v_sub_f32_e32 v160, v160, v167
	v_exp_f32_e32 v164, v162
	v_exp_f32_e32 v222, v160
	v_cvt_pk_bf16_f32 v160, v163, v178
	v_mov_b32_e32 v248, v167
	v_pk_mul_f32 v[66:67], v[66:67], v[164:165] op_sel_hi:[1,0]
	v_pk_mul_f32 v[64:65], v[64:65], v[164:165] op_sel_hi:[1,0]
	v_pk_mul_f32 v[58:59], v[58:59], v[164:165] op_sel_hi:[1,0]
	v_pk_mul_f32 v[56:57], v[56:57], v[164:165] op_sel_hi:[1,0]
	v_pk_mul_f32 v[50:51], v[50:51], v[164:165] op_sel_hi:[1,0]
	v_pk_mul_f32 v[48:49], v[48:49], v[164:165] op_sel_hi:[1,0]
	v_pk_mul_f32 v[38:39], v[38:39], v[164:165] op_sel_hi:[1,0]
	v_pk_mul_f32 v[36:37], v[36:37], v[164:165] op_sel_hi:[1,0]
	v_pk_mul_f32 v[30:31], v[30:31], v[164:165] op_sel_hi:[1,0]
	v_pk_mul_f32 v[28:29], v[28:29], v[164:165] op_sel_hi:[1,0]
	v_pk_mul_f32 v[22:23], v[22:23], v[164:165] op_sel_hi:[1,0]
	v_pk_mul_f32 v[20:21], v[20:21], v[164:165] op_sel_hi:[1,0]
	v_pk_mul_f32 v[14:15], v[14:15], v[164:165] op_sel_hi:[1,0]
	v_pk_mul_f32 v[12:13], v[12:13], v[164:165] op_sel_hi:[1,0]
	v_pk_mul_f32 v[6:7], v[6:7], v[164:165] op_sel_hi:[1,0]
	v_pk_mul_f32 v[4:5], v[4:5], v[164:165] op_sel_hi:[1,0]
	v_add_f32_e32 v223, v222, v161
	v_cvt_pk_bf16_f32 v161, v218, v219
	v_cvt_pk_bf16_f32 v162, v166, v165
	v_cvt_pk_bf16_f32 v163, v179, v222
	v_fmac_f32_e32 v223, v206, v164
	v_mfma_f32_16x16x32_bf16 v[64:67], v[124:127], v[160:163], v[64:67]
	v_mov_b32_e32 v206, v223
	v_mfma_f32_16x16x32_bf16 v[56:59], v[116:119], v[160:163], v[56:59]
	v_mfma_f32_16x16x32_bf16 v[48:51], v[120:123], v[160:163], v[48:51]
	v_mfma_f32_16x16x32_bf16 v[36:39], v[108:111], v[160:163], v[36:39]
	v_mfma_f32_16x16x32_bf16 v[28:31], v[112:115], v[160:163], v[28:31]
	v_mfma_f32_16x16x32_bf16 v[20:23], v[104:107], v[160:163], v[20:23]
	v_mfma_f32_16x16x32_bf16 v[12:15], v[100:103], v[160:163], v[12:15]
	v_mfma_f32_16x16x32_bf16 v[4:7], v[96:99], v[160:163], v[4:7]
; #define MFMA16(a, b, c) __builtin_amdgcn_mfma_f32_16x16x32_bf16((a), (b), (c), 0, 0, 0)
; __device__ __forceinline__ void attn_compute(const AttnK& C, const AttnV& V, const bf16x8 (&qf)[4], f32x4 (&o)[8], float& mrun, float& lsum, int lane, int g,
;                                              bool masked, int keycol0, int cs, const LAS float* brow  , int cq) {
;     ...
; #pragma unroll
;     for (int T = 0; T < 2; ++T) { s[T] = (f32x4){0.f, 0.f, 0.f, 0.f};
; #pragma unroll
;         for (int dc = 0; dc < 4; ++dc) s[T] = MFMA16(C.kf[T][dc], qf[dc], s[T]); }
;     if (masked) {
; #pragma unroll
;         for (int T = 0; T < 2; ++T)
; #pragma unroll
;             for (int i = 0; i < 4; ++i) { const int keycol = keycol0 + 8 * g + 4 * T + i; const bool ok = keycol >= cs && keycol < cs + 16;
;                 const int dcol = keycol - cq + 15; const float bv = brow[ok ? dcol : 0];
;                 s[T][i] = ok ? s[T][i] + bv : -1e30f; }
;     }
.LBB0_609:
	s_cmp_lt_u32 s78, s79
	s_cbranch_scc1 .LBB0_590
	s_waitcnt vmcnt(0)
	v_mfma_f32_16x16x32_bf16 v[128:131], v[128:131], v[72:75], 0
	v_mfma_f32_16x16x32_bf16 v[128:131], v[132:135], v[76:79], v[128:131]
	v_mfma_f32_16x16x32_bf16 v[128:131], v[136:139], v[88:91], v[128:131]
	v_mov_b32_e32 v136, 0xf149f2ca
	v_mov_b32_e32 v137, 0xf149f2ca
	v_mfma_f32_16x16x32_bf16 v[132:135], v[140:143], v[92:95], v[128:131]
	v_mfma_f32_16x16x32_bf16 v[128:131], v[148:151], v[72:75], 0
	v_mfma_f32_16x16x32_bf16 v[128:131], v[152:155], v[76:79], v[128:131]
	v_mfma_f32_16x16x32_bf16 v[128:131], v[156:159], v[88:91], v[128:131]
	v_mfma_f32_16x16x32_bf16 v[128:131], v[144:147], v[92:95], v[128:131]
	ds_read_b32 v137, v249
	ds_read_b32 v136, v249 offset:4
	ds_read_b32 v138, v249 offset:8
	ds_read_b32 v140, v249 offset:12
	ds_read_b32 v141, v249 offset:16
	ds_read_b32 v142, v249 offset:20
	ds_read_b32 v143, v249 offset:24
	ds_read_b32 v144, v249 offset:28
	v_mov_b32_e32 v145, 0xf149f2ca
	s_waitcnt lgkmcnt(0)
	v_add_f32_e32 v137, v132, v137
	v_add_f32_e32 v136, v133, v136
	v_add_f32_e32 v138, v134, v138
	v_add_f32_e32 v140, v135, v140
	v_add_f32_e32 v141, v128, v141
	v_add_f32_e32 v142, v129, v142
	v_add_f32_e32 v143, v130, v143
	v_add_f32_e32 v144, v131, v144
	v_cndmask_b32_e64 v137, v145, v137, s[18:19]
	v_cndmask_b32_e64 v136, v145, v136, s[20:21]
	v_cndmask_b32_e64 v138, v145, v138, s[22:23]
	v_cndmask_b32_e64 v132, v145, v140, s[24:25]
	v_cndmask_b32_e64 v134, v145, v141, s[26:27]
	v_cndmask_b32_e64 v133, v145, v142, s[28:29]
	v_cndmask_b32_e64 v129, v145, v143, s[30:31]
	v_cndmask_b32_e64 v128, v145, v144, s[34:35]
	s_mov_b64 s[38:39], exec
	s_branch .LBB0_589
